# phase1-single-pass-with-item-loop
# baseline (speedup 1.0000x reference)
; __device__ void phase1(const Params& p, LAS unsigned char* lds) {
;     ...
;     for (int it = blockIdx.x; it < M / 128; it += gridDim.x) {
;         const size_t r0 = (size_t)it * 128; const int b = (int)(r0 / SEQ); const bool has_halo = (r0 % SEQ) != 0;
;     ...
;         const f32x4 g4 = *(const f32x4*)(p.n1g + tid * 4);
;         const f32x4 sc = *(const f32x4*)(mod + (size_t)b * MODW + 1 * D + tid * 4), sh = *(const f32x4*)(mod + (size_t)b * MODW + 0 * D + tid * 4);
;         const f32x4 gs = g4 * (sc + 1.0f);
.LBB0_134:
	s_mov_b32 s0, 0
	s_andn2_b64 vcc, exec, s[14:15]
	s_cbranch_vccnz .LBB0_223
	s_mov_b32 s35, s2
.Lp1_item:
	v_readlane_b32 s4, v255, 3
	v_readlane_b32 s5, v255, 4
	v_lshlrev_b32_e32 v12, 4, v235
	v_readfirstlane_b32 s69, v235
	s_nop 3
	s_load_dwordx2 s[6:7], s[4:5], 0x0
	s_load_dwordx2 s[8:9], s[4:5], 0x20
	s_load_dwordx2 s[12:13], s[4:5], 0x90
	s_lshr_b32 s16, s35, 7
	s_and_b32 s18, s35, 0x7f
	s_lshr_b32 s69, s69, 7
	v_add_u32_e32 v13, 0x2000, v12
	s_waitcnt lgkmcnt(0)
	s_mul_i32 s19, s16, 0xc000
	s_add_u32 s20, s12, 0xa600000
	s_addc_u32 s21, s13, 0
	s_add_u32 s20, s20, s19
	s_addc_u32 s21, s21, 0
	global_load_dwordx4 v[16:19], v12, s[20:21]
	global_load_dwordx4 v[20:23], v13, s[20:21]
	global_load_dwordx4 v[24:27], v12, s[8:9]
	s_lshl_b32 s19, s35, 20
	s_add_u32 s30, s6, s19
	s_addc_u32 s31, s7, 0
	s_lshl_b32 s19, s35, 19
	s_add_u32 s36, s12, 0xa630000
	s_addc_u32 s37, s13, 0
	s_add_u32 s36, s36, s19
	s_addc_u32 s37, s37, 0
	s_mov_b32 s40, 8
	s_mov_b64 s[38:39], -1
	s_mov_b32 s41, 1
	s_cmp_eq_u32 s18, 0
	s_cbranch_scc1 .Lp1_nohalo
	s_mov_b32 s40, 9
	s_mov_b64 s[38:39], 0
	s_mov_b32 s41, 0
	s_sub_u32 s30, s30, 0x20000
	s_subb_u32 s31, s31, 0

; __device__ void phase1(const Params& p, LAS unsigned char* lds) {
;     ...
;     for (int it = blockIdx.x; it < M / 128; it += gridDim.x) {
.Lp1_noadv:
	s_mov_b64 s[38:39], -1
	s_mov_b32 s41, 0
	s_sub_u32 s40, s40, 1
	s_cmp_lg_u32 s40, 0
	s_cbranch_scc1 .Lp1_group
	s_add_i32 s35, s35, s10
	s_cmpk_lt_i32 s35, 0x100
	s_cbranch_scc1 .Lp1_item
	s_branch .LBB0_223
